# SwiGLU main K-loop: LDS-DMA loads use SGPR-base + 32-bit VGPR offset form, 64-bit VALU address adds removed
# speedup vs baseline: 1.0263x; 1.0012x over previous
.LBB0_255:
	s_ashr_i32 s15, s14, 31
	s_lshl_b64 s[20:21], s[14:15], 19
	s_add_u32 s42, s31, s20
	s_addc_u32 s43, s34, s21
	s_and_b64 s[20:21], s[4:5], exec
	s_cselect_b32 s15, s43, s53
	s_cselect_b32 s20, s42, s52
	s_ashr_i32 s13, s12, 31
	s_lshl_b64 s[50:51], s[12:13], 19
	s_add_u32 s50, s35, s50
	s_addc_u32 s51, s36, s51
	s_and_b64 s[58:59], s[4:5], exec
	s_cselect_b32 s13, s51, s57
	s_cselect_b32 s21, s50, s56
	s_add_u32 s52, s52, 0x40080
	s_addc_u32 s53, s53, 0
	s_add_u32 s73, s56, 0x100
	s_addc_u32 s75, s57, 0
	s_mov_b32 s82, -2
	s_add_u32 s0, s52, 0xfffc0080
	s_addc_u32 s56, s53, -1
	s_add_i32 s83, 0, 0x10000
	s_cmp_eq_u32 s82, 12
	s_cselect_b32 s59, s15, s56
	s_cselect_b32 s58, s20, s0
	s_cselect_b32 s57, s13, s75
	s_cselect_b32 s56, s21, s73
	s_add_i32 s0, 0, 0x14000
	v_add_u32_e32 v94, s83, v171
	v_add_u32_e32 v155, s0, v171
	ds_read_b128 v[74:77], v94
	ds_read_b128 v[78:81], v94 offset:1024
	ds_read_b128 v[90:93], v94 offset:2048
	ds_read_b128 v[94:97], v94 offset:3072
	ds_read_b128 v[180:183], v155
	ds_read_b128 v[184:187], v155 offset:1024
	ds_read_b128 v[188:191], v155 offset:2048
	ds_read_b128 v[192:195], v155 offset:3072
	s_add_i32 m0, s61, 0xc000
	ds_read_b128 v[196:199], v177
	ds_read_b128 v[200:203], v177 offset:1024
	ds_read_b128 v[204:207], v177 offset:2048
	ds_read_b128 v[208:211], v177 offset:3072
	ds_read_b128 v[212:215], v177 offset:4096
	ds_read_b128 v[216:219], v177 offset:5120
	ds_read_b128 v[230:233], v177 offset:6144
	ds_read_b128 v[238:241], v177 offset:7168
	global_load_lds_dwordx4 v164, s[52:53]
	s_add_i32 m0, s61, 0xe000
	s_nop 0
	global_load_lds_dwordx4 v166, s[52:53]
	s_waitcnt vmcnt(8)
	s_waitcnt lgkmcnt(0)
	s_barrier
	s_setprio 1
	s_waitcnt lgkmcnt(0)
	v_mfma_f32_16x16x32_bf16 v[142:145], v[74:77], v[196:199], 0
	v_mfma_f32_16x16x32_bf16 v[134:137], v[90:93], v[196:199], 0
	v_mfma_f32_16x16x32_bf16 v[126:129], v[74:77], v[204:207], 0
	v_mfma_f32_16x16x32_bf16 v[118:121], v[90:93], v[204:207], 0
	v_mfma_f32_16x16x32_bf16 v[110:113], v[74:77], v[212:215], 0
	v_mfma_f32_16x16x32_bf16 v[102:105], v[90:93], v[212:215], 0
	v_mfma_f32_16x16x32_bf16 v[86:89], v[74:77], v[230:233], 0
	v_mfma_f32_16x16x32_bf16 v[70:73], v[90:93], v[230:233], 0
	v_mfma_f32_16x16x32_bf16 v[142:145], v[78:81], v[200:203], v[142:145]
	v_mfma_f32_16x16x32_bf16 v[134:137], v[94:97], v[200:203], v[134:137]
	v_mfma_f32_16x16x32_bf16 v[126:129], v[78:81], v[208:211], v[126:129]
	v_mfma_f32_16x16x32_bf16 v[118:121], v[94:97], v[208:211], v[118:121]
	v_mfma_f32_16x16x32_bf16 v[110:113], v[78:81], v[216:219], v[110:113]
	v_mfma_f32_16x16x32_bf16 v[102:105], v[94:97], v[216:219], v[102:105]
	v_mfma_f32_16x16x32_bf16 v[86:89], v[78:81], v[238:241], v[86:89]
	v_mfma_f32_16x16x32_bf16 v[70:73], v[94:97], v[238:241], v[70:73]
	s_setprio 0
	s_setprio 1
	v_mfma_f32_16x16x32_bf16 v[138:141], v[180:183], v[196:199], 0
	v_mfma_f32_16x16x32_bf16 v[130:133], v[188:191], v[196:199], 0
	v_mfma_f32_16x16x32_bf16 v[122:125], v[180:183], v[204:207], 0
	v_mfma_f32_16x16x32_bf16 v[114:117], v[188:191], v[204:207], 0
	v_mfma_f32_16x16x32_bf16 v[106:109], v[180:183], v[212:215], 0
	v_mfma_f32_16x16x32_bf16 v[98:101], v[188:191], v[212:215], 0
	v_mfma_f32_16x16x32_bf16 v[82:85], v[180:183], v[230:233], 0
	v_mfma_f32_16x16x32_bf16 v[66:69], v[188:191], v[230:233], 0
	v_mfma_f32_16x16x32_bf16 v[138:141], v[184:187], v[200:203], v[138:141]
	v_mfma_f32_16x16x32_bf16 v[130:133], v[192:195], v[200:203], v[130:133]
	v_mfma_f32_16x16x32_bf16 v[122:125], v[184:187], v[208:211], v[122:125]
	v_mfma_f32_16x16x32_bf16 v[114:117], v[192:195], v[208:211], v[114:117]
	v_mfma_f32_16x16x32_bf16 v[106:109], v[184:187], v[216:219], v[106:109]
	v_mfma_f32_16x16x32_bf16 v[98:101], v[192:195], v[216:219], v[98:101]
	v_mfma_f32_16x16x32_bf16 v[82:85], v[184:187], v[238:241], v[82:85]
	v_mfma_f32_16x16x32_bf16 v[66:69], v[192:195], v[238:241], v[66:69]
	s_setprio 0
	s_barrier
	s_add_i32 s83, s83, s37
	s_add_u32 s98, s56, s76
	s_addc_u32 s99, s57, s77
	s_mov_b32 m0, s83
	ds_read_b128 v[196:199], v177 offset:16384
	ds_read_b128 v[200:203], v177 offset:17408
	ds_read_b128 v[204:207], v177 offset:18432
	ds_read_b128 v[208:211], v177 offset:19456
	ds_read_b128 v[212:215], v177 offset:20480
	ds_read_b128 v[216:219], v177 offset:21504
	ds_read_b128 v[230:233], v177 offset:22528
	ds_read_b128 v[238:241], v177 offset:23552
	global_load_lds_dwordx4 v150, s[56:57]
	s_add_i32 m0, s83, 0x2000
	s_add_u32 s84, s56, 0x40000
	s_addc_u32 s85, s57, 0
	s_add_i32 s0, s0, s37
	global_load_lds_dwordx4 v146, s[56:57]
	s_mov_b32 m0, s0
	s_add_u32 s100, s58, s76
	s_addc_u32 s101, s59, s77
	global_load_lds_dwordx4 v150, s[84:85]
	s_add_i32 m0, s0, 0x2000
	s_nop 0
	global_load_lds_dwordx4 v146, s[84:85]
	s_mov_b32 m0, s61
	s_nop 0
	global_load_lds_dwordx4 v152, s[58:59]
	s_mov_b32 m0, s64
	s_nop 0
	global_load_lds_dwordx4 v148, s[58:59]
	s_waitcnt vmcnt(8)
	s_waitcnt lgkmcnt(0)
	s_barrier
	s_setprio 1
	s_waitcnt lgkmcnt(0)
	v_mfma_f32_16x16x32_bf16 v[62:65], v[74:77], v[196:199], 0
	v_mfma_f32_16x16x32_bf16 v[54:57], v[90:93], v[196:199], 0
	v_mfma_f32_16x16x32_bf16 v[46:49], v[74:77], v[204:207], 0
	v_mfma_f32_16x16x32_bf16 v[38:41], v[90:93], v[204:207], 0
	v_mfma_f32_16x16x32_bf16 v[30:33], v[74:77], v[212:215], 0
	v_mfma_f32_16x16x32_bf16 v[22:25], v[90:93], v[212:215], 0
	v_mfma_f32_16x16x32_bf16 v[14:17], v[74:77], v[230:233], 0
	v_mfma_f32_16x16x32_bf16 v[6:9], v[90:93], v[230:233], 0
	v_mfma_f32_16x16x32_bf16 v[62:65], v[78:81], v[200:203], v[62:65]
	v_mfma_f32_16x16x32_bf16 v[54:57], v[94:97], v[200:203], v[54:57]
	v_mfma_f32_16x16x32_bf16 v[46:49], v[78:81], v[208:211], v[46:49]
	v_mfma_f32_16x16x32_bf16 v[38:41], v[94:97], v[208:211], v[38:41]
	v_mfma_f32_16x16x32_bf16 v[30:33], v[78:81], v[216:219], v[30:33]
	v_mfma_f32_16x16x32_bf16 v[22:25], v[94:97], v[216:219], v[22:25]
	v_mfma_f32_16x16x32_bf16 v[14:17], v[78:81], v[238:241], v[14:17]
	v_mfma_f32_16x16x32_bf16 v[6:9], v[94:97], v[238:241], v[6:9]
	s_setprio 0
	s_setprio 1
	v_mfma_f32_16x16x32_bf16 v[58:61], v[180:183], v[196:199], 0
	v_mfma_f32_16x16x32_bf16 v[50:53], v[188:191], v[196:199], 0
	v_mfma_f32_16x16x32_bf16 v[42:45], v[180:183], v[204:207], 0
	v_mfma_f32_16x16x32_bf16 v[34:37], v[188:191], v[204:207], 0
	v_mfma_f32_16x16x32_bf16 v[26:29], v[180:183], v[212:215], 0
	v_mfma_f32_16x16x32_bf16 v[18:21], v[188:191], v[212:215], 0
	v_mfma_f32_16x16x32_bf16 v[10:13], v[180:183], v[230:233], 0
	v_mfma_f32_16x16x32_bf16 v[2:5], v[188:191], v[230:233], 0
	v_mfma_f32_16x16x32_bf16 v[58:61], v[184:187], v[200:203], v[58:61]
	v_mfma_f32_16x16x32_bf16 v[50:53], v[192:195], v[200:203], v[50:53]
	v_mfma_f32_16x16x32_bf16 v[42:45], v[184:187], v[208:211], v[42:45]
	v_mfma_f32_16x16x32_bf16 v[34:37], v[192:195], v[208:211], v[34:37]
	v_mfma_f32_16x16x32_bf16 v[26:29], v[184:187], v[216:219], v[26:29]
	v_mfma_f32_16x16x32_bf16 v[18:21], v[192:195], v[216:219], v[18:21]
	v_mfma_f32_16x16x32_bf16 v[10:13], v[184:187], v[238:241], v[10:13]
	v_mfma_f32_16x16x32_bf16 v[2:5], v[192:195], v[238:241], v[2:5]
	s_setprio 0
	s_barrier
	s_add_i32 s0, 0, 0x18000
	s_add_i32 s83, 0, 0x1c000
	v_add_u32_e32 v94, s0, v171
	v_add_u32_e32 v155, s83, v171
	ds_read_b128 v[74:77], v94
	ds_read_b128 v[78:81], v94 offset:1024
	ds_read_b128 v[90:93], v94 offset:2048
	ds_read_b128 v[94:97], v94 offset:3072
	ds_read_b128 v[180:183], v155
	ds_read_b128 v[184:187], v155 offset:1024
	ds_read_b128 v[188:191], v155 offset:2048
	ds_read_b128 v[192:195], v155 offset:3072
	s_add_u32 s58, s58, 0x40000
	s_addc_u32 s59, s59, 0
	s_mov_b32 m0, s65
	ds_read_b128 v[196:199], v177 offset:32768
	ds_read_b128 v[200:203], v177 offset:33792
	ds_read_b128 v[204:207], v177 offset:34816
	ds_read_b128 v[208:211], v177 offset:35840
	ds_read_b128 v[212:215], v177 offset:36864
	ds_read_b128 v[216:219], v177 offset:37888
	ds_read_b128 v[230:233], v177 offset:38912
	ds_read_b128 v[238:241], v177 offset:39936
	global_load_lds_dwordx4 v152, s[58:59]
	s_mov_b32 m0, s66
	s_nop 0
	global_load_lds_dwordx4 v148, s[58:59]
	s_waitcnt vmcnt(8)
	s_waitcnt lgkmcnt(0)
	s_barrier
	s_setprio 1
	s_waitcnt lgkmcnt(0)
	v_mfma_f32_16x16x32_bf16 v[142:145], v[74:77], v[196:199], v[142:145]
	v_mfma_f32_16x16x32_bf16 v[134:137], v[90:93], v[196:199], v[134:137]
	v_mfma_f32_16x16x32_bf16 v[126:129], v[74:77], v[204:207], v[126:129]
	v_mfma_f32_16x16x32_bf16 v[118:121], v[90:93], v[204:207], v[118:121]
	v_mfma_f32_16x16x32_bf16 v[110:113], v[74:77], v[212:215], v[110:113]
	v_mfma_f32_16x16x32_bf16 v[102:105], v[90:93], v[212:215], v[102:105]
	v_mfma_f32_16x16x32_bf16 v[86:89], v[74:77], v[230:233], v[86:89]
	v_mfma_f32_16x16x32_bf16 v[70:73], v[90:93], v[230:233], v[70:73]
	v_mfma_f32_16x16x32_bf16 v[142:145], v[78:81], v[200:203], v[142:145]
	v_mfma_f32_16x16x32_bf16 v[134:137], v[94:97], v[200:203], v[134:137]
	v_mfma_f32_16x16x32_bf16 v[126:129], v[78:81], v[208:211], v[126:129]
	v_mfma_f32_16x16x32_bf16 v[118:121], v[94:97], v[208:211], v[118:121]
	v_mfma_f32_16x16x32_bf16 v[110:113], v[78:81], v[216:219], v[110:113]
	v_mfma_f32_16x16x32_bf16 v[102:105], v[94:97], v[216:219], v[102:105]
	v_mfma_f32_16x16x32_bf16 v[86:89], v[78:81], v[238:241], v[86:89]
	v_mfma_f32_16x16x32_bf16 v[70:73], v[94:97], v[238:241], v[70:73]
	s_setprio 0
	s_setprio 1
	v_mfma_f32_16x16x32_bf16 v[138:141], v[180:183], v[196:199], v[138:141]
	v_mfma_f32_16x16x32_bf16 v[130:133], v[188:191], v[196:199], v[130:133]
	v_mfma_f32_16x16x32_bf16 v[122:125], v[180:183], v[204:207], v[122:125]
	v_mfma_f32_16x16x32_bf16 v[114:117], v[188:191], v[204:207], v[114:117]
	v_mfma_f32_16x16x32_bf16 v[106:109], v[180:183], v[212:215], v[106:109]
	v_mfma_f32_16x16x32_bf16 v[98:101], v[188:191], v[212:215], v[98:101]
	v_mfma_f32_16x16x32_bf16 v[82:85], v[180:183], v[230:233], v[82:85]
	v_mfma_f32_16x16x32_bf16 v[66:69], v[188:191], v[230:233], v[66:69]
	v_mfma_f32_16x16x32_bf16 v[138:141], v[184:187], v[200:203], v[138:141]
	v_mfma_f32_16x16x32_bf16 v[130:133], v[192:195], v[200:203], v[130:133]
	v_mfma_f32_16x16x32_bf16 v[122:125], v[184:187], v[208:211], v[122:125]
	v_mfma_f32_16x16x32_bf16 v[114:117], v[192:195], v[208:211], v[114:117]
	v_mfma_f32_16x16x32_bf16 v[106:109], v[184:187], v[216:219], v[106:109]
	v_mfma_f32_16x16x32_bf16 v[98:101], v[192:195], v[216:219], v[98:101]
	v_mfma_f32_16x16x32_bf16 v[82:85], v[184:187], v[238:241], v[82:85]
	v_mfma_f32_16x16x32_bf16 v[66:69], v[192:195], v[238:241], v[66:69]
	s_setprio 0
	s_barrier
	s_add_i32 s0, s0, s37
	s_mov_b32 m0, s0
	ds_read_b128 v[196:199], v177 offset:49152
	ds_read_b128 v[200:203], v177 offset:50176
	ds_read_b128 v[204:207], v177 offset:51200
	ds_read_b128 v[208:211], v177 offset:52224
	ds_read_b128 v[212:215], v177 offset:53248
	ds_read_b128 v[216:219], v177 offset:54272
	ds_read_b128 v[230:233], v177 offset:55296
	ds_read_b128 v[238:241], v177 offset:56320
	global_load_lds_dwordx4 v150, s[98:99]
	s_add_i32 m0, s0, 0x2000
	s_add_u32 s56, s56, 0x40080
	s_addc_u32 s57, s57, 0
	s_add_i32 s0, s83, s37
	global_load_lds_dwordx4 v146, s[98:99]
	s_mov_b32 m0, s0
	s_nop 0
	global_load_lds_dwordx4 v150, s[56:57]
	s_add_i32 m0, s0, 0x2000
	s_nop 0
	global_load_lds_dwordx4 v146, s[56:57]
	s_mov_b32 m0, s67
	s_nop 0
	global_load_lds_dwordx4 v152, s[100:101]
	s_mov_b32 m0, s68
	s_nop 0
	global_load_lds_dwordx4 v148, s[100:101]
	s_waitcnt vmcnt(8)
	s_waitcnt lgkmcnt(0)
	s_barrier
	s_setprio 1
	s_waitcnt lgkmcnt(0)
	v_mfma_f32_16x16x32_bf16 v[62:65], v[74:77], v[196:199], v[62:65]
	v_mfma_f32_16x16x32_bf16 v[54:57], v[90:93], v[196:199], v[54:57]
	v_mfma_f32_16x16x32_bf16 v[46:49], v[74:77], v[204:207], v[46:49]
	v_mfma_f32_16x16x32_bf16 v[38:41], v[90:93], v[204:207], v[38:41]
	v_mfma_f32_16x16x32_bf16 v[30:33], v[74:77], v[212:215], v[30:33]
	v_mfma_f32_16x16x32_bf16 v[22:25], v[90:93], v[212:215], v[22:25]
	v_mfma_f32_16x16x32_bf16 v[14:17], v[74:77], v[230:233], v[14:17]
	v_mfma_f32_16x16x32_bf16 v[6:9], v[90:93], v[230:233], v[6:9]
	v_mfma_f32_16x16x32_bf16 v[62:65], v[78:81], v[200:203], v[62:65]
	v_mfma_f32_16x16x32_bf16 v[54:57], v[94:97], v[200:203], v[54:57]
	v_mfma_f32_16x16x32_bf16 v[46:49], v[78:81], v[208:211], v[46:49]
	v_mfma_f32_16x16x32_bf16 v[38:41], v[94:97], v[208:211], v[38:41]
	v_mfma_f32_16x16x32_bf16 v[30:33], v[78:81], v[216:219], v[30:33]
	v_mfma_f32_16x16x32_bf16 v[22:25], v[94:97], v[216:219], v[22:25]
	v_mfma_f32_16x16x32_bf16 v[14:17], v[78:81], v[238:241], v[14:17]
	v_mfma_f32_16x16x32_bf16 v[6:9], v[94:97], v[238:241], v[6:9]
	s_setprio 0
	s_setprio 1
	v_mfma_f32_16x16x32_bf16 v[58:61], v[180:183], v[196:199], v[58:61]
	v_mfma_f32_16x16x32_bf16 v[50:53], v[188:191], v[196:199], v[50:53]
	v_mfma_f32_16x16x32_bf16 v[42:45], v[180:183], v[204:207], v[42:45]
	v_mfma_f32_16x16x32_bf16 v[34:37], v[188:191], v[204:207], v[34:37]
	v_mfma_f32_16x16x32_bf16 v[26:29], v[180:183], v[212:215], v[26:29]
	v_mfma_f32_16x16x32_bf16 v[18:21], v[188:191], v[212:215], v[18:21]
	v_mfma_f32_16x16x32_bf16 v[10:13], v[180:183], v[230:233], v[10:13]
	v_mfma_f32_16x16x32_bf16 v[2:5], v[188:191], v[230:233], v[2:5]
	v_mfma_f32_16x16x32_bf16 v[58:61], v[184:187], v[200:203], v[58:61]
	v_mfma_f32_16x16x32_bf16 v[50:53], v[192:195], v[200:203], v[50:53]
	v_mfma_f32_16x16x32_bf16 v[42:45], v[184:187], v[208:211], v[42:45]
	v_mfma_f32_16x16x32_bf16 v[34:37], v[192:195], v[208:211], v[34:37]
	v_mfma_f32_16x16x32_bf16 v[26:29], v[184:187], v[216:219], v[26:29]
	v_mfma_f32_16x16x32_bf16 v[18:21], v[192:195], v[216:219], v[18:21]
	v_mfma_f32_16x16x32_bf16 v[10:13], v[184:187], v[238:241], v[10:13]
	v_mfma_f32_16x16x32_bf16 v[2:5], v[192:195], v[238:241], v[2:5]
	s_setprio 0
	s_barrier
	s_add_i32 s82, s82, 2
	s_add_u32 s52, s52, 0x100
	s_addc_u32 s53, s53, 0
	s_add_u32 s73, s73, 0x100
	s_addc_u32 s75, s75, 0
.LBB0_256:
	s_add_u32 s0, s52, 0xfffc0080
	s_addc_u32 s56, s53, -1
	s_add_i32 s83, 0, 0x10000
	s_cmp_eq_u32 s82, 12
	s_cselect_b32 s59, s15, s56
	s_cselect_b32 s58, s20, s0
	s_cselect_b32 s57, s13, s75
	s_cselect_b32 s56, s21, s73
	s_add_i32 s0, 0, 0x14000
	v_add_u32_e32 v94, s83, v171
	v_add_u32_e32 v155, s0, v171
	ds_read_b128 v[74:77], v94
	ds_read_b128 v[78:81], v94 offset:1024
	ds_read_b128 v[90:93], v94 offset:2048
	ds_read_b128 v[94:97], v94 offset:3072
	ds_read_b128 v[180:183], v155
	ds_read_b128 v[184:187], v155 offset:1024
	ds_read_b128 v[188:191], v155 offset:2048
	ds_read_b128 v[192:195], v155 offset:3072
	s_add_i32 m0, s61, 0xc000
	ds_read_b128 v[196:199], v177
	ds_read_b128 v[200:203], v177 offset:1024
	ds_read_b128 v[204:207], v177 offset:2048
	ds_read_b128 v[208:211], v177 offset:3072
	ds_read_b128 v[212:215], v177 offset:4096
	ds_read_b128 v[216:219], v177 offset:5120
	ds_read_b128 v[230:233], v177 offset:6144
	ds_read_b128 v[238:241], v177 offset:7168
	global_load_lds_dwordx4 v164, s[52:53]
	s_add_i32 m0, s61, 0xe000
	s_nop 0
	global_load_lds_dwordx4 v166, s[52:53]
	s_waitcnt vmcnt(8)
	s_waitcnt lgkmcnt(0)
	s_barrier
	s_setprio 1
	s_waitcnt lgkmcnt(0)
	v_mfma_f32_16x16x32_bf16 v[142:145], v[74:77], v[196:199], v[142:145]
	v_mfma_f32_16x16x32_bf16 v[134:137], v[90:93], v[196:199], v[134:137]
	v_mfma_f32_16x16x32_bf16 v[126:129], v[74:77], v[204:207], v[126:129]
	v_mfma_f32_16x16x32_bf16 v[118:121], v[90:93], v[204:207], v[118:121]
	v_mfma_f32_16x16x32_bf16 v[110:113], v[74:77], v[212:215], v[110:113]
	v_mfma_f32_16x16x32_bf16 v[102:105], v[90:93], v[212:215], v[102:105]
	v_mfma_f32_16x16x32_bf16 v[86:89], v[74:77], v[230:233], v[86:89]
	v_mfma_f32_16x16x32_bf16 v[70:73], v[90:93], v[230:233], v[70:73]
	v_mfma_f32_16x16x32_bf16 v[142:145], v[78:81], v[200:203], v[142:145]
	v_mfma_f32_16x16x32_bf16 v[134:137], v[94:97], v[200:203], v[134:137]
	v_mfma_f32_16x16x32_bf16 v[126:129], v[78:81], v[208:211], v[126:129]
	v_mfma_f32_16x16x32_bf16 v[118:121], v[94:97], v[208:211], v[118:121]
	v_mfma_f32_16x16x32_bf16 v[110:113], v[78:81], v[216:219], v[110:113]
	v_mfma_f32_16x16x32_bf16 v[102:105], v[94:97], v[216:219], v[102:105]
	v_mfma_f32_16x16x32_bf16 v[86:89], v[78:81], v[238:241], v[86:89]
	v_mfma_f32_16x16x32_bf16 v[70:73], v[94:97], v[238:241], v[70:73]
	s_setprio 0
	s_setprio 1
	v_mfma_f32_16x16x32_bf16 v[138:141], v[180:183], v[196:199], v[138:141]
	v_mfma_f32_16x16x32_bf16 v[130:133], v[188:191], v[196:199], v[130:133]
	v_mfma_f32_16x16x32_bf16 v[122:125], v[180:183], v[204:207], v[122:125]
	v_mfma_f32_16x16x32_bf16 v[114:117], v[188:191], v[204:207], v[114:117]
	v_mfma_f32_16x16x32_bf16 v[106:109], v[180:183], v[212:215], v[106:109]
	v_mfma_f32_16x16x32_bf16 v[98:101], v[188:191], v[212:215], v[98:101]
	v_mfma_f32_16x16x32_bf16 v[82:85], v[180:183], v[230:233], v[82:85]
	v_mfma_f32_16x16x32_bf16 v[66:69], v[188:191], v[230:233], v[66:69]
	v_mfma_f32_16x16x32_bf16 v[138:141], v[184:187], v[200:203], v[138:141]
	v_mfma_f32_16x16x32_bf16 v[130:133], v[192:195], v[200:203], v[130:133]
	v_mfma_f32_16x16x32_bf16 v[122:125], v[184:187], v[208:211], v[122:125]
	v_mfma_f32_16x16x32_bf16 v[114:117], v[192:195], v[208:211], v[114:117]
	v_mfma_f32_16x16x32_bf16 v[106:109], v[184:187], v[216:219], v[106:109]
	v_mfma_f32_16x16x32_bf16 v[98:101], v[192:195], v[216:219], v[98:101]
	v_mfma_f32_16x16x32_bf16 v[82:85], v[184:187], v[238:241], v[82:85]
	v_mfma_f32_16x16x32_bf16 v[66:69], v[192:195], v[238:241], v[66:69]
	s_setprio 0
	s_barrier
	s_add_i32 s83, s83, s37
	s_add_u32 s98, s56, s76
	s_addc_u32 s99, s57, s77
	s_mov_b32 m0, s83
	ds_read_b128 v[196:199], v177 offset:16384
	ds_read_b128 v[200:203], v177 offset:17408
	ds_read_b128 v[204:207], v177 offset:18432
	ds_read_b128 v[208:211], v177 offset:19456
	ds_read_b128 v[212:215], v177 offset:20480
	ds_read_b128 v[216:219], v177 offset:21504
	ds_read_b128 v[230:233], v177 offset:22528
	ds_read_b128 v[238:241], v177 offset:23552
	global_load_lds_dwordx4 v150, s[56:57]
	s_add_i32 m0, s83, 0x2000
	s_add_u32 s84, s56, 0x40000
	s_addc_u32 s85, s57, 0
	s_add_i32 s0, s0, s37
	global_load_lds_dwordx4 v146, s[56:57]
	s_mov_b32 m0, s0
	s_add_u32 s100, s58, s76
	s_addc_u32 s101, s59, s77
	global_load_lds_dwordx4 v150, s[84:85]
	s_add_i32 m0, s0, 0x2000
	s_nop 0
	global_load_lds_dwordx4 v146, s[84:85]
	s_mov_b32 m0, s61
	s_nop 0
	global_load_lds_dwordx4 v152, s[58:59]
	s_mov_b32 m0, s64
	s_nop 0
	global_load_lds_dwordx4 v148, s[58:59]
	s_waitcnt vmcnt(8)
	s_waitcnt lgkmcnt(0)
	s_barrier
	s_setprio 1
	s_waitcnt lgkmcnt(0)
	v_mfma_f32_16x16x32_bf16 v[62:65], v[74:77], v[196:199], v[62:65]
	v_mfma_f32_16x16x32_bf16 v[54:57], v[90:93], v[196:199], v[54:57]
	v_mfma_f32_16x16x32_bf16 v[46:49], v[74:77], v[204:207], v[46:49]
	v_mfma_f32_16x16x32_bf16 v[38:41], v[90:93], v[204:207], v[38:41]
	v_mfma_f32_16x16x32_bf16 v[30:33], v[74:77], v[212:215], v[30:33]
	v_mfma_f32_16x16x32_bf16 v[22:25], v[90:93], v[212:215], v[22:25]
	v_mfma_f32_16x16x32_bf16 v[14:17], v[74:77], v[230:233], v[14:17]
	v_mfma_f32_16x16x32_bf16 v[6:9], v[90:93], v[230:233], v[6:9]
	v_mfma_f32_16x16x32_bf16 v[62:65], v[78:81], v[200:203], v[62:65]
	v_mfma_f32_16x16x32_bf16 v[54:57], v[94:97], v[200:203], v[54:57]
	v_mfma_f32_16x16x32_bf16 v[46:49], v[78:81], v[208:211], v[46:49]
	v_mfma_f32_16x16x32_bf16 v[38:41], v[94:97], v[208:211], v[38:41]
	v_mfma_f32_16x16x32_bf16 v[30:33], v[78:81], v[216:219], v[30:33]
	v_mfma_f32_16x16x32_bf16 v[22:25], v[94:97], v[216:219], v[22:25]
	v_mfma_f32_16x16x32_bf16 v[14:17], v[78:81], v[238:241], v[14:17]
	v_mfma_f32_16x16x32_bf16 v[6:9], v[94:97], v[238:241], v[6:9]
	s_setprio 0
	s_setprio 1
	v_mfma_f32_16x16x32_bf16 v[58:61], v[180:183], v[196:199], v[58:61]
	v_mfma_f32_16x16x32_bf16 v[50:53], v[188:191], v[196:199], v[50:53]
	v_mfma_f32_16x16x32_bf16 v[42:45], v[180:183], v[204:207], v[42:45]
	v_mfma_f32_16x16x32_bf16 v[34:37], v[188:191], v[204:207], v[34:37]
	v_mfma_f32_16x16x32_bf16 v[26:29], v[180:183], v[212:215], v[26:29]
	v_mfma_f32_16x16x32_bf16 v[18:21], v[188:191], v[212:215], v[18:21]
	v_mfma_f32_16x16x32_bf16 v[10:13], v[180:183], v[230:233], v[10:13]
	v_mfma_f32_16x16x32_bf16 v[2:5], v[188:191], v[230:233], v[2:5]
	v_mfma_f32_16x16x32_bf16 v[58:61], v[184:187], v[200:203], v[58:61]
	v_mfma_f32_16x16x32_bf16 v[50:53], v[192:195], v[200:203], v[50:53]
	v_mfma_f32_16x16x32_bf16 v[42:45], v[184:187], v[208:211], v[42:45]
	v_mfma_f32_16x16x32_bf16 v[34:37], v[192:195], v[208:211], v[34:37]
	v_mfma_f32_16x16x32_bf16 v[26:29], v[184:187], v[216:219], v[26:29]
	v_mfma_f32_16x16x32_bf16 v[18:21], v[192:195], v[216:219], v[18:21]
	v_mfma_f32_16x16x32_bf16 v[10:13], v[184:187], v[238:241], v[10:13]
	v_mfma_f32_16x16x32_bf16 v[2:5], v[192:195], v[238:241], v[2:5]
	s_setprio 0
	s_barrier
	s_add_i32 s0, 0, 0x18000
	s_add_i32 s83, 0, 0x1c000
	v_add_u32_e32 v94, s0, v171
	v_add_u32_e32 v155, s83, v171
	ds_read_b128 v[74:77], v94
	ds_read_b128 v[78:81], v94 offset:1024
	ds_read_b128 v[90:93], v94 offset:2048
	ds_read_b128 v[94:97], v94 offset:3072
	ds_read_b128 v[180:183], v155
	ds_read_b128 v[184:187], v155 offset:1024
	ds_read_b128 v[188:191], v155 offset:2048
	ds_read_b128 v[192:195], v155 offset:3072
	s_add_u32 s58, s58, 0x40000
	s_addc_u32 s59, s59, 0
	s_mov_b32 m0, s65
	ds_read_b128 v[196:199], v177 offset:32768
	ds_read_b128 v[200:203], v177 offset:33792
	ds_read_b128 v[204:207], v177 offset:34816
	ds_read_b128 v[208:211], v177 offset:35840
	ds_read_b128 v[212:215], v177 offset:36864
	ds_read_b128 v[216:219], v177 offset:37888
	ds_read_b128 v[230:233], v177 offset:38912
	ds_read_b128 v[238:241], v177 offset:39936
	global_load_lds_dwordx4 v152, s[58:59]
	s_mov_b32 m0, s66
	s_nop 0
	global_load_lds_dwordx4 v148, s[58:59]
	s_waitcnt vmcnt(8)
	s_waitcnt lgkmcnt(0)
	s_barrier
	s_setprio 1
	s_waitcnt lgkmcnt(0)
	v_mfma_f32_16x16x32_bf16 v[142:145], v[74:77], v[196:199], v[142:145]
	v_mfma_f32_16x16x32_bf16 v[134:137], v[90:93], v[196:199], v[134:137]
	v_mfma_f32_16x16x32_bf16 v[126:129], v[74:77], v[204:207], v[126:129]
	v_mfma_f32_16x16x32_bf16 v[118:121], v[90:93], v[204:207], v[118:121]
	v_mfma_f32_16x16x32_bf16 v[110:113], v[74:77], v[212:215], v[110:113]
	v_mfma_f32_16x16x32_bf16 v[102:105], v[90:93], v[212:215], v[102:105]
	v_mfma_f32_16x16x32_bf16 v[86:89], v[74:77], v[230:233], v[86:89]
	v_mfma_f32_16x16x32_bf16 v[70:73], v[90:93], v[230:233], v[70:73]
	v_mfma_f32_16x16x32_bf16 v[142:145], v[78:81], v[200:203], v[142:145]
	v_mfma_f32_16x16x32_bf16 v[134:137], v[94:97], v[200:203], v[134:137]
	v_mfma_f32_16x16x32_bf16 v[126:129], v[78:81], v[208:211], v[126:129]
	v_mfma_f32_16x16x32_bf16 v[118:121], v[94:97], v[208:211], v[118:121]
	v_mfma_f32_16x16x32_bf16 v[110:113], v[78:81], v[216:219], v[110:113]
	v_mfma_f32_16x16x32_bf16 v[102:105], v[94:97], v[216:219], v[102:105]
	v_mfma_f32_16x16x32_bf16 v[86:89], v[78:81], v[238:241], v[86:89]
	v_mfma_f32_16x16x32_bf16 v[70:73], v[94:97], v[238:241], v[70:73]
	s_setprio 0
	s_setprio 1
	v_mfma_f32_16x16x32_bf16 v[138:141], v[180:183], v[196:199], v[138:141]
	v_mfma_f32_16x16x32_bf16 v[130:133], v[188:191], v[196:199], v[130:133]
	v_mfma_f32_16x16x32_bf16 v[122:125], v[180:183], v[204:207], v[122:125]
	v_mfma_f32_16x16x32_bf16 v[114:117], v[188:191], v[204:207], v[114:117]
	v_mfma_f32_16x16x32_bf16 v[106:109], v[180:183], v[212:215], v[106:109]
	v_mfma_f32_16x16x32_bf16 v[98:101], v[188:191], v[212:215], v[98:101]
	v_mfma_f32_16x16x32_bf16 v[82:85], v[180:183], v[230:233], v[82:85]
	v_mfma_f32_16x16x32_bf16 v[66:69], v[188:191], v[230:233], v[66:69]
	v_mfma_f32_16x16x32_bf16 v[138:141], v[184:187], v[200:203], v[138:141]
	v_mfma_f32_16x16x32_bf16 v[130:133], v[192:195], v[200:203], v[130:133]
	v_mfma_f32_16x16x32_bf16 v[122:125], v[184:187], v[208:211], v[122:125]
	v_mfma_f32_16x16x32_bf16 v[114:117], v[192:195], v[208:211], v[114:117]
	v_mfma_f32_16x16x32_bf16 v[106:109], v[184:187], v[216:219], v[106:109]
	v_mfma_f32_16x16x32_bf16 v[98:101], v[192:195], v[216:219], v[98:101]
	v_mfma_f32_16x16x32_bf16 v[82:85], v[184:187], v[238:241], v[82:85]
	v_mfma_f32_16x16x32_bf16 v[66:69], v[192:195], v[238:241], v[66:69]
	s_setprio 0
	s_barrier
	s_add_i32 s0, s0, s37
	s_mov_b32 m0, s0
	ds_read_b128 v[196:199], v177 offset:49152
	ds_read_b128 v[200:203], v177 offset:50176
	ds_read_b128 v[204:207], v177 offset:51200
	ds_read_b128 v[208:211], v177 offset:52224
	ds_read_b128 v[212:215], v177 offset:53248
	ds_read_b128 v[216:219], v177 offset:54272
	ds_read_b128 v[230:233], v177 offset:55296
	ds_read_b128 v[238:241], v177 offset:56320
	global_load_lds_dwordx4 v150, s[98:99]
	s_add_i32 m0, s0, 0x2000
	s_add_u32 s56, s56, 0x40080
	s_addc_u32 s57, s57, 0
	s_add_i32 s0, s83, s37
	global_load_lds_dwordx4 v146, s[98:99]
	s_mov_b32 m0, s0
	s_nop 0
	global_load_lds_dwordx4 v150, s[56:57]
	s_add_i32 m0, s0, 0x2000
	s_nop 0
	global_load_lds_dwordx4 v146, s[56:57]
	s_mov_b32 m0, s67
	s_nop 0
	global_load_lds_dwordx4 v152, s[100:101]
	s_mov_b32 m0, s68
	s_nop 0
	global_load_lds_dwordx4 v148, s[100:101]
	s_waitcnt vmcnt(8)
	s_waitcnt lgkmcnt(0)
	s_barrier
	s_setprio 1
	s_waitcnt lgkmcnt(0)
	v_mfma_f32_16x16x32_bf16 v[62:65], v[74:77], v[196:199], v[62:65]
	v_mfma_f32_16x16x32_bf16 v[54:57], v[90:93], v[196:199], v[54:57]
	v_mfma_f32_16x16x32_bf16 v[46:49], v[74:77], v[204:207], v[46:49]
	v_mfma_f32_16x16x32_bf16 v[38:41], v[90:93], v[204:207], v[38:41]
	v_mfma_f32_16x16x32_bf16 v[30:33], v[74:77], v[212:215], v[30:33]
	v_mfma_f32_16x16x32_bf16 v[22:25], v[90:93], v[212:215], v[22:25]
	v_mfma_f32_16x16x32_bf16 v[14:17], v[74:77], v[230:233], v[14:17]
	v_mfma_f32_16x16x32_bf16 v[6:9], v[90:93], v[230:233], v[6:9]
	v_mfma_f32_16x16x32_bf16 v[62:65], v[78:81], v[200:203], v[62:65]
	v_mfma_f32_16x16x32_bf16 v[54:57], v[94:97], v[200:203], v[54:57]
	v_mfma_f32_16x16x32_bf16 v[46:49], v[78:81], v[208:211], v[46:49]
	v_mfma_f32_16x16x32_bf16 v[38:41], v[94:97], v[208:211], v[38:41]
	v_mfma_f32_16x16x32_bf16 v[30:33], v[78:81], v[216:219], v[30:33]
	v_mfma_f32_16x16x32_bf16 v[22:25], v[94:97], v[216:219], v[22:25]
	v_mfma_f32_16x16x32_bf16 v[14:17], v[78:81], v[238:241], v[14:17]
	v_mfma_f32_16x16x32_bf16 v[6:9], v[94:97], v[238:241], v[6:9]
	s_setprio 0
	s_setprio 1
	v_mfma_f32_16x16x32_bf16 v[58:61], v[180:183], v[196:199], v[58:61]
	v_mfma_f32_16x16x32_bf16 v[50:53], v[188:191], v[196:199], v[50:53]
	v_mfma_f32_16x16x32_bf16 v[42:45], v[180:183], v[204:207], v[42:45]
	v_mfma_f32_16x16x32_bf16 v[34:37], v[188:191], v[204:207], v[34:37]
	v_mfma_f32_16x16x32_bf16 v[26:29], v[180:183], v[212:215], v[26:29]
	v_mfma_f32_16x16x32_bf16 v[18:21], v[188:191], v[212:215], v[18:21]
	v_mfma_f32_16x16x32_bf16 v[10:13], v[180:183], v[230:233], v[10:13]
	v_mfma_f32_16x16x32_bf16 v[2:5], v[188:191], v[230:233], v[2:5]
	v_mfma_f32_16x16x32_bf16 v[58:61], v[184:187], v[200:203], v[58:61]
	v_mfma_f32_16x16x32_bf16 v[50:53], v[192:195], v[200:203], v[50:53]
	v_mfma_f32_16x16x32_bf16 v[42:45], v[184:187], v[208:211], v[42:45]
	v_mfma_f32_16x16x32_bf16 v[34:37], v[192:195], v[208:211], v[34:37]
	v_mfma_f32_16x16x32_bf16 v[26:29], v[184:187], v[216:219], v[26:29]
	v_mfma_f32_16x16x32_bf16 v[18:21], v[192:195], v[216:219], v[18:21]
	v_mfma_f32_16x16x32_bf16 v[10:13], v[184:187], v[238:241], v[10:13]
	v_mfma_f32_16x16x32_bf16 v[2:5], v[192:195], v[238:241], v[2:5]
	s_setprio 0
	s_barrier
	s_add_i32 s82, s82, 2
	s_add_u32 s52, s52, 0x100
	s_addc_u32 s53, s53, 0
	s_add_u32 s73, s73, 0x100
	s_addc_u32 s75, s75, 0
	s_cmp_gt_u32 s82, 13
	s_cbranch_scc0 .LBB0_256
	s_and_b64 vcc, exec, s[10:11]
	s_cbranch_vccz .LBB0_259
	s_barrier
